# cross-attention: the 8 second-partial q loads issued together instead of one round trip each
# speedup vs baseline: 1.0448x; 1.0008x over previous
; #define GAS __attribute__((address_space(1)))
; __device__ __forceinline__ unsigned cvtpk(float lo, float hi) { unsigned r; asm volatile("v_cvt_pk_bf16_f32 %0, %1, %2" : "=v"(r) : "v"(lo), "v"(hi)); return r; }
;   __device__ __forceinline__ size_t q2off() const { return (size_t)(WS_XQ2 - WS_XQ) / 2; }
; template <class P> __device__ __forceinline__ void attn_phase(P pol, LAS unsigned char* L, int G) {
;     ...
;     } else { const bf16* Qp = pol.Q + (size_t)qb * P::LDQ + (unsigned)(qi * strd * P::LDQ + hoff + hi * 8);
;       const u64 ssq = pol.ss[qb + qi * strd];
;       u32x4 qw[8]; float ss = 0.f;
; #pragma unroll
;       for (int d0 = 0; d0 < 8; ++d0) qw[d0] = *(const GAS u32x4*)(Qp + d0 * 16);
;       if (P::Q_PARTS2) {
; #pragma unroll
;         for (int d0 = 0; d0 < 8; ++d0) { const u32x4 q2 = *(const GAS u32x4*)(Qp + pol.q2off() + d0 * 16);
; #pragma unroll
;           for (int e = 0; e < 4; ++e) qw[d0][e] = cvtpk(bflo(qw[d0][e]) + bflo(q2[e]), bfhi(qw[d0][e]) + bfhi(q2[e])); } }
.LBB0_704:
	s_lshl_b32 s0, s18, 6
	s_and_b32 s1, s0, 0xffffff00
	s_addk_i32 s0, 0xe000
	s_lshr_b32 s0, s0, 3
	s_lshl_b32 s2, s18, 7
	s_and_b32 s0, s0, 0x1fffff00
	s_and_b32 s19, s2, 0x180
	s_add_i32 s4, s1, s17
	s_add_i32 s2, s0, 0x100
	s_cmpk_gt_i32 s1, 0x1fff
	s_cselect_b32 s2, s2, 0
	s_ashr_i32 s3, s2, 31
	s_lshl_b64 s[8:9], s[2:3], 11
	v_or_b32_e32 v2, s19, v126
	s_add_u32 s8, s10, s8
	v_add_u32_e32 v116, 0x8000, v2
	s_addc_u32 s9, s11, s9
	v_mov_b32_e32 v117, v3
	s_ashr_i32 s5, s4, 31
	v_lshl_add_u64 v[12:13], v[2:3], 1, s[8:9]
	v_lshl_add_u64 v[16:17], v[116:117], 1, s[8:9]
	s_lshl_b64 s[8:9], s[4:5], 9
	s_lshl_b64 s[22:23], s[4:5], 10
	s_add_u32 s22, s12, s22
	v_or_b32_e32 v20, s19, v127
	s_addc_u32 s23, s13, s23
	v_lshlrev_b32_e32 v20, 1, v20
	v_mov_b32_e32 v21, v3
	v_lshl_add_u64 v[50:51], s[22:23], 0, v[20:21]
	v_add_u32_e32 v22, s4, v125
	s_mov_b32 s1, 0x1b000000
	v_ashrrev_i32_e32 v23, 31, v22
	v_add_co_u32_e64 v50, s[4:5], s1, v50
	v_lshl_add_u64 v[22:23], v[22:23], 3, s[6:7]
	s_nop 0
	v_addc_co_u32_e64 v51, s[4:5], 0, v51, s[4:5]
	global_load_dwordx4 v[8:11], v[12:13], off
	global_load_dwordx4 v[4:7], v[16:17], off
	s_nop 0
	global_load_dwordx4 v[12:15], v[12:13], off offset:1024
	s_nop 0
	global_load_dwordx4 v[16:19], v[16:17], off offset:1024
	s_nop 0
	global_load_dwordx2 v[48:49], v[22:23], off
	global_load_dwordx4 v[52:55], v20, s[22:23]
	global_load_dwordx4 v[44:47], v20, s[22:23] offset:32
	global_load_dwordx4 v[40:43], v20, s[22:23] offset:64
	global_load_dwordx4 v[36:39], v20, s[22:23] offset:96
	global_load_dwordx4 v[32:35], v20, s[22:23] offset:128
	global_load_dwordx4 v[28:31], v20, s[22:23] offset:160
	global_load_dwordx4 v[24:27], v20, s[22:23] offset:192
	s_nop 0
	global_load_dwordx4 v[20:23], v20, s[22:23] offset:224
	v_readlane_b32 s1, v253, 41
	global_load_dwordx4 v[168:171], v[50:51], off
	global_load_dwordx4 v[172:175], v[50:51], off offset:32
	global_load_dwordx4 v[176:179], v[50:51], off offset:64
	global_load_dwordx4 v[180:183], v[50:51], off offset:96
	global_load_dwordx4 v[184:187], v[50:51], off offset:128
	global_load_dwordx4 v[188:191], v[50:51], off offset:160
	global_load_dwordx4 v[192:195], v[50:51], off offset:192
	global_load_dwordx4 v[196:199], v[50:51], off offset:224
	v_add_u32_e32 v158, s16, v120
	v_mov_b32_e32 v159, 0
	s_mov_b32 s0, 0
	s_or_b32 s2, s2, 64
	s_waitcnt vmcnt(15)
	v_lshlrev_b32_e32 v61, 16, v52
	v_and_b32_e32 v52, 0xffff0000, v52
	s_waitcnt vmcnt(7)
	v_mov_b32_e32 v56, v168
	v_mov_b32_e32 v57, v169
	v_mov_b32_e32 v58, v170
	v_mov_b32_e32 v59, v171
	v_lshlrev_b32_e32 v60, 16, v56
	v_and_b32_e32 v56, 0xffff0000, v56
	v_add_f32_e32 v60, v60, v61
	v_add_f32_e32 v52, v56, v52
	v_cvt_pk_bf16_f32 v52, v60, v52
	v_lshlrev_b32_e32 v56, 16, v57
	v_lshlrev_b32_e32 v60, 16, v53
	v_and_b32_e32 v57, 0xffff0000, v57
	v_and_b32_e32 v53, 0xffff0000, v53
	v_add_f32_e32 v56, v56, v60
	v_add_f32_e32 v53, v57, v53
	v_cvt_pk_bf16_f32 v53, v56, v53
	v_lshlrev_b32_e32 v56, 16, v58
	v_lshlrev_b32_e32 v57, 16, v54
	v_add_f32_e32 v56, v56, v57
	v_and_b32_e32 v57, 0xffff0000, v58
	v_and_b32_e32 v54, 0xffff0000, v54
	v_add_f32_e32 v54, v57, v54
	v_cvt_pk_bf16_f32 v54, v56, v54
	v_lshlrev_b32_e32 v56, 16, v59
	v_lshlrev_b32_e32 v57, 16, v55
	v_add_f32_e32 v56, v56, v57
	v_and_b32_e32 v57, 0xffff0000, v59
	v_and_b32_e32 v55, 0xffff0000, v55
	v_add_f32_e32 v55, v57, v55
	v_cvt_pk_bf16_f32 v55, v56, v55
	v_lshlrev_b32_e32 v61, 16, v44
	v_and_b32_e32 v44, 0xffff0000, v44
	s_waitcnt vmcnt(6)
	v_mov_b32_e32 v56, v172
	v_mov_b32_e32 v57, v173
	v_mov_b32_e32 v58, v174
	v_mov_b32_e32 v59, v175
	v_lshlrev_b32_e32 v60, 16, v56
	v_and_b32_e32 v56, 0xffff0000, v56
	v_add_f32_e32 v60, v60, v61
	v_add_f32_e32 v44, v56, v44
	v_cvt_pk_bf16_f32 v44, v60, v44
	v_lshlrev_b32_e32 v56, 16, v57
	v_lshlrev_b32_e32 v60, 16, v45
	v_and_b32_e32 v57, 0xffff0000, v57
	v_and_b32_e32 v45, 0xffff0000, v45
	v_add_f32_e32 v56, v56, v60
	v_add_f32_e32 v45, v57, v45
	v_cvt_pk_bf16_f32 v45, v56, v45
	v_lshlrev_b32_e32 v56, 16, v58
	v_lshlrev_b32_e32 v57, 16, v46
	v_add_f32_e32 v56, v56, v57
	v_and_b32_e32 v57, 0xffff0000, v58
	v_and_b32_e32 v46, 0xffff0000, v46
	v_add_f32_e32 v46, v57, v46
	v_cvt_pk_bf16_f32 v46, v56, v46
	v_lshlrev_b32_e32 v56, 16, v59
	v_lshlrev_b32_e32 v57, 16, v47
	v_add_f32_e32 v56, v56, v57
	v_and_b32_e32 v57, 0xffff0000, v59
	v_and_b32_e32 v47, 0xffff0000, v47
	v_add_f32_e32 v47, v57, v47
	v_cvt_pk_bf16_f32 v47, v56, v47
	v_lshlrev_b32_e32 v61, 16, v40
	v_and_b32_e32 v40, 0xffff0000, v40
	s_waitcnt vmcnt(5)
	v_mov_b32_e32 v56, v176
	v_mov_b32_e32 v57, v177
	v_mov_b32_e32 v58, v178
	v_mov_b32_e32 v59, v179
	v_lshlrev_b32_e32 v60, 16, v56
	v_and_b32_e32 v56, 0xffff0000, v56
	v_add_f32_e32 v60, v60, v61
	v_add_f32_e32 v40, v56, v40
	v_cvt_pk_bf16_f32 v40, v60, v40
	v_lshlrev_b32_e32 v56, 16, v57
	v_lshlrev_b32_e32 v60, 16, v41
	v_and_b32_e32 v57, 0xffff0000, v57
	v_and_b32_e32 v41, 0xffff0000, v41
	v_add_f32_e32 v56, v56, v60
	v_add_f32_e32 v41, v57, v41
	v_cvt_pk_bf16_f32 v41, v56, v41
	v_lshlrev_b32_e32 v56, 16, v58
	v_lshlrev_b32_e32 v57, 16, v42
	v_add_f32_e32 v56, v56, v57
	v_and_b32_e32 v57, 0xffff0000, v58
	v_and_b32_e32 v42, 0xffff0000, v42
	v_add_f32_e32 v42, v57, v42
	v_cvt_pk_bf16_f32 v42, v56, v42
	v_lshlrev_b32_e32 v56, 16, v59
	v_lshlrev_b32_e32 v57, 16, v43
	v_add_f32_e32 v56, v56, v57
	v_and_b32_e32 v57, 0xffff0000, v59
	v_and_b32_e32 v43, 0xffff0000, v43
	v_add_f32_e32 v43, v57, v43
	v_cvt_pk_bf16_f32 v43, v56, v43
	v_lshlrev_b32_e32 v61, 16, v36
	v_and_b32_e32 v36, 0xffff0000, v36
	s_waitcnt vmcnt(4)
; #define GAS __attribute__((address_space(1)))
; __device__ __forceinline__ unsigned cvtpk(float lo, float hi) { unsigned r; asm volatile("v_cvt_pk_bf16_f32 %0, %1, %2" : "=v"(r) : "v"(lo), "v"(hi)); return r; }
; __device__ __forceinline__ float u64f(u64 v) { return (float)(unsigned)(v >> 32) * 4294967296.f + (float)(unsigned)v; }
;   __device__ __forceinline__ size_t q2off() const { return (size_t)(WS_XQ2 - WS_XQ) / 2; }
; template <class P> __device__ __forceinline__ void attn_phase(P pol, LAS unsigned char* L, int G) {
;     ...
;       if (P::Q_PARTS2) {
; #pragma unroll
;         for (int d0 = 0; d0 < 8; ++d0) { const u32x4 q2 = *(const GAS u32x4*)(Qp + pol.q2off() + d0 * 16);
; #pragma unroll
;           for (int e = 0; e < 4; ++e) qw[d0][e] = cvtpk(bflo(qw[d0][e]) + bflo(q2[e]), bfhi(qw[d0][e]) + bfhi(q2[e])); } }
;       const float varq = u64f(ssq) * SS_INV + RMS_EPS;
; #pragma unroll
;       for (int d0 = 0; d0 < 8; ++d0)
; #pragma unroll
;         for (int e = 0; e < 4; ++e) { const float a = bflo(qw[d0][e]), b = bfhi(qw[d0][e]); ss += a * a + b * b; }
	v_mov_b32_e32 v56, v180
	v_mov_b32_e32 v57, v181
	v_mov_b32_e32 v58, v182
	v_mov_b32_e32 v59, v183
	v_lshlrev_b32_e32 v60, 16, v56
	v_and_b32_e32 v56, 0xffff0000, v56
	v_add_f32_e32 v60, v60, v61
	v_add_f32_e32 v36, v56, v36
	v_cvt_pk_bf16_f32 v36, v60, v36
	v_lshlrev_b32_e32 v56, 16, v57
	v_lshlrev_b32_e32 v60, 16, v37
	v_and_b32_e32 v57, 0xffff0000, v57
	v_and_b32_e32 v37, 0xffff0000, v37
	v_add_f32_e32 v56, v56, v60
	v_add_f32_e32 v37, v57, v37
	v_cvt_pk_bf16_f32 v37, v56, v37
	v_lshlrev_b32_e32 v56, 16, v58
	v_lshlrev_b32_e32 v57, 16, v38
	v_add_f32_e32 v56, v56, v57
	v_and_b32_e32 v57, 0xffff0000, v58
	v_and_b32_e32 v38, 0xffff0000, v38
	v_add_f32_e32 v38, v57, v38
	v_cvt_pk_bf16_f32 v38, v56, v38
	v_lshlrev_b32_e32 v56, 16, v59
	v_lshlrev_b32_e32 v57, 16, v39
	v_add_f32_e32 v56, v56, v57
	v_and_b32_e32 v57, 0xffff0000, v59
	v_and_b32_e32 v39, 0xffff0000, v39
	v_add_f32_e32 v39, v57, v39
	v_cvt_pk_bf16_f32 v39, v56, v39
	v_lshlrev_b32_e32 v61, 16, v32
	v_and_b32_e32 v32, 0xffff0000, v32
	v_and_b32_e32 v67, 0xffff0000, v36
	v_and_b32_e32 v69, 0xffff0000, v37
	v_lshlrev_b32_e32 v68, 16, v37
	v_and_b32_e32 v71, 0xffff0000, v38
	v_lshlrev_b32_e32 v70, 16, v38
	v_and_b32_e32 v73, 0xffff0000, v39
	v_lshlrev_b32_e32 v72, 16, v39
	s_waitcnt vmcnt(3)
	v_mov_b32_e32 v56, v184
	v_mov_b32_e32 v57, v185
	v_mov_b32_e32 v58, v186
	v_mov_b32_e32 v59, v187
	v_lshlrev_b32_e32 v60, 16, v56
	v_and_b32_e32 v56, 0xffff0000, v56
	v_add_f32_e32 v60, v60, v61
	v_add_f32_e32 v32, v56, v32
	v_cvt_pk_bf16_f32 v32, v60, v32
	v_lshlrev_b32_e32 v56, 16, v57
	v_lshlrev_b32_e32 v60, 16, v33
	v_and_b32_e32 v57, 0xffff0000, v57
	v_and_b32_e32 v33, 0xffff0000, v33
	v_add_f32_e32 v56, v56, v60
	v_add_f32_e32 v33, v57, v33
	v_cvt_pk_bf16_f32 v33, v56, v33
	v_lshlrev_b32_e32 v56, 16, v58
	v_lshlrev_b32_e32 v57, 16, v34
	v_add_f32_e32 v56, v56, v57
	v_and_b32_e32 v57, 0xffff0000, v58
	v_and_b32_e32 v34, 0xffff0000, v34
	v_add_f32_e32 v34, v57, v34
	v_cvt_pk_bf16_f32 v34, v56, v34
	v_lshlrev_b32_e32 v56, 16, v59
	v_lshlrev_b32_e32 v57, 16, v35
	v_add_f32_e32 v56, v56, v57
	v_and_b32_e32 v57, 0xffff0000, v59
	v_and_b32_e32 v35, 0xffff0000, v35
	v_add_f32_e32 v35, v57, v35
	v_cvt_pk_bf16_f32 v35, v56, v35
	v_lshlrev_b32_e32 v61, 16, v28
	v_and_b32_e32 v28, 0xffff0000, v28
	v_and_b32_e32 v75, 0xffff0000, v32
	v_lshlrev_b32_e32 v74, 16, v32
	v_mul_f32_e32 v32, v75, v75
	v_fmac_f32_e32 v32, v74, v74
	v_and_b32_e32 v77, 0xffff0000, v33
	v_lshlrev_b32_e32 v76, 16, v33
	v_and_b32_e32 v79, 0xffff0000, v34
	v_lshlrev_b32_e32 v78, 16, v34
	v_and_b32_e32 v81, 0xffff0000, v35
	v_lshlrev_b32_e32 v80, 16, v35
	s_waitcnt vmcnt(2)
	v_mov_b32_e32 v56, v188
	v_mov_b32_e32 v57, v189
	v_mov_b32_e32 v58, v190
	v_mov_b32_e32 v59, v191
	v_lshlrev_b32_e32 v60, 16, v56
	v_and_b32_e32 v56, 0xffff0000, v56
	v_add_f32_e32 v60, v60, v61
	v_add_f32_e32 v28, v56, v28
	v_cvt_pk_bf16_f32 v28, v60, v28
	v_lshlrev_b32_e32 v56, 16, v57
	v_lshlrev_b32_e32 v60, 16, v29
	v_and_b32_e32 v57, 0xffff0000, v57
	v_and_b32_e32 v29, 0xffff0000, v29
	v_add_f32_e32 v56, v56, v60
	v_add_f32_e32 v29, v57, v29
	v_cvt_pk_bf16_f32 v29, v56, v29
	v_lshlrev_b32_e32 v56, 16, v58
	v_lshlrev_b32_e32 v57, 16, v30
	v_add_f32_e32 v56, v56, v57
	v_and_b32_e32 v57, 0xffff0000, v58
	v_and_b32_e32 v30, 0xffff0000, v30
	v_add_f32_e32 v30, v57, v30
	v_cvt_pk_bf16_f32 v30, v56, v30
	v_lshlrev_b32_e32 v56, 16, v59
	v_lshlrev_b32_e32 v57, 16, v31
	v_add_f32_e32 v56, v56, v57
	v_and_b32_e32 v57, 0xffff0000, v59
	v_and_b32_e32 v31, 0xffff0000, v31
	v_add_f32_e32 v31, v57, v31
	v_cvt_pk_bf16_f32 v31, v56, v31
	v_lshlrev_b32_e32 v61, 16, v24
	v_and_b32_e32 v24, 0xffff0000, v24
	v_and_b32_e32 v83, 0xffff0000, v28
	v_lshlrev_b32_e32 v82, 16, v28
	v_mul_f32_e32 v28, v83, v83
	v_fmac_f32_e32 v28, v82, v82
	v_and_b32_e32 v85, 0xffff0000, v29
	v_lshlrev_b32_e32 v84, 16, v29
	v_and_b32_e32 v87, 0xffff0000, v30
	v_lshlrev_b32_e32 v86, 16, v30
	v_and_b32_e32 v89, 0xffff0000, v31
	v_lshlrev_b32_e32 v88, 16, v31
	s_waitcnt vmcnt(1)
	v_mov_b32_e32 v56, v192
	v_mov_b32_e32 v57, v193
	v_mov_b32_e32 v58, v194
	v_mov_b32_e32 v59, v195
	v_lshlrev_b32_e32 v60, 16, v56
	v_and_b32_e32 v56, 0xffff0000, v56
	v_add_f32_e32 v60, v60, v61
	v_add_f32_e32 v24, v56, v24
	v_cvt_pk_bf16_f32 v24, v60, v24
	v_lshlrev_b32_e32 v56, 16, v57
	v_lshlrev_b32_e32 v60, 16, v25
	v_and_b32_e32 v57, 0xffff0000, v57
	v_and_b32_e32 v25, 0xffff0000, v25
	v_add_f32_e32 v56, v56, v60
	v_add_f32_e32 v25, v57, v25
	v_cvt_pk_bf16_f32 v25, v56, v25
	v_lshlrev_b32_e32 v56, 16, v58
	v_lshlrev_b32_e32 v57, 16, v26
	v_add_f32_e32 v56, v56, v57
	v_and_b32_e32 v57, 0xffff0000, v58
	v_and_b32_e32 v26, 0xffff0000, v26
	v_add_f32_e32 v26, v57, v26
	v_cvt_pk_bf16_f32 v26, v56, v26
	v_lshlrev_b32_e32 v56, 16, v59
	v_lshlrev_b32_e32 v57, 16, v27
	v_add_f32_e32 v56, v56, v57
	v_and_b32_e32 v57, 0xffff0000, v59
	v_and_b32_e32 v27, 0xffff0000, v27
	v_add_f32_e32 v27, v57, v27
	v_cvt_pk_bf16_f32 v27, v56, v27
	v_lshlrev_b32_e32 v51, 16, v20
	v_and_b32_e32 v20, 0xffff0000, v20
	v_and_b32_e32 v91, 0xffff0000, v24
	v_lshlrev_b32_e32 v90, 16, v24
	v_mul_f32_e32 v24, v91, v91
	v_fmac_f32_e32 v24, v90, v90
	v_and_b32_e32 v93, 0xffff0000, v25
	v_lshlrev_b32_e32 v92, 16, v25
	v_and_b32_e32 v95, 0xffff0000, v26
	v_lshlrev_b32_e32 v94, 16, v26
	v_and_b32_e32 v97, 0xffff0000, v27
	v_lshlrev_b32_e32 v96, 16, v27
	s_waitcnt vmcnt(0)
; #define GAS __attribute__((address_space(1)))
; #define LAS __attribute__((address_space(3)))
; __device__ __forceinline__ unsigned cvtpk(float lo, float hi) { unsigned r; asm volatile("v_cvt_pk_bf16_f32 %0, %1, %2" : "=v"(r) : "v"(lo), "v"(hi)); return r; }
; __device__ __forceinline__ float pl32_sum(float v) { auto rr = __builtin_amdgcn_permlane32_swap(__float_as_uint(v), __float_as_uint(v), false, false); return __uint_as_float(rr[0]) + __uint_as_float(rr[1]); }
; __device__ __forceinline__ float u64f(u64 v) { return (float)(unsigned)(v >> 32) * 4294967296.f + (float)(unsigned)v; }
;   __device__ __forceinline__ size_t q2off() const { return (size_t)(WS_XQ2 - WS_XQ) / 2; }
; template <class P> __device__ __forceinline__ void attn_phase(P pol, LAS unsigned char* L, int G) {
;     ...
; #pragma unroll
;         for (int d0 = 0; d0 < 8; ++d0) { const u32x4 q2 = *(const GAS u32x4*)(Qp + pol.q2off() + d0 * 16);
; #pragma unroll
;           for (int e = 0; e < 4; ++e) qw[d0][e] = cvtpk(bflo(qw[d0][e]) + bflo(q2[e]), bfhi(qw[d0][e]) + bfhi(q2[e])); } }
;       const float varq = u64f(ssq) * SS_INV + RMS_EPS;
; #pragma unroll
;       for (int d0 = 0; d0 < 8; ++d0)
; #pragma unroll
;         for (int e = 0; e < 4; ++e) { const float a = bflo(qw[d0][e]), b = bfhi(qw[d0][e]); ss += a * a + b * b; }
;       ss = pl32_sum(ss);
;       const float rq = __builtin_amdgcn_rsqf(ss * (1.f / HD) + RMS_EPS * varq);
; #pragma unroll
;       for (int d0 = 0; d0 < 8; ++d0) { const f32x4 g0 = *(const LAS f32x4*)(gq + d0 * 16 + hi * 8), g1 = *(const LAS f32x4*)(gq + d0 * 16 + hi * 8 + 4); u32x4 w;
;         w[0] = cvtpk(bflo(qw[d0][0]) * rq * g0[0], bfhi(qw[d0][0]) * rq * g0[1]); w[1] = cvtpk(bflo(qw[d0][1]) * rq * g0[2], bfhi(qw[d0][1]) * rq * g0[3]);
;         w[2] = cvtpk(bflo(qw[d0][2]) * rq * g1[0], bfhi(qw[d0][2]) * rq * g1[1]); w[3] = cvtpk(bflo(qw[d0][3]) * rq * g1[2], bfhi(qw[d0][3]) * rq * g1[3]);
	v_mov_b32_e32 v56, v196
	v_mov_b32_e32 v57, v197
	v_mov_b32_e32 v58, v198
	v_mov_b32_e32 v59, v199
	v_lshlrev_b32_e32 v50, 16, v56
	v_add_f32_e32 v50, v50, v51
	v_and_b32_e32 v51, 0xffff0000, v56
	v_add_f32_e32 v20, v51, v20
	v_cvt_pk_bf16_f32 v50, v50, v20
	v_lshlrev_b32_e32 v20, 16, v57
	v_lshlrev_b32_e32 v51, 16, v21
	v_add_f32_e32 v20, v20, v51
	v_and_b32_e32 v51, 0xffff0000, v57
	v_and_b32_e32 v21, 0xffff0000, v21
	v_add_f32_e32 v21, v51, v21
	v_cvt_pk_bf16_f32 v51, v20, v21
	v_lshlrev_b32_e32 v20, 16, v58
	v_lshlrev_b32_e32 v21, 16, v22
	v_add_f32_e32 v20, v20, v21
	v_and_b32_e32 v21, 0xffff0000, v58
	v_and_b32_e32 v22, 0xffff0000, v22
	v_add_f32_e32 v21, v21, v22
	v_cvt_pk_bf16_f32 v22, v20, v21
	v_lshlrev_b32_e32 v20, 16, v59
	v_lshlrev_b32_e32 v21, 16, v23
	v_add_f32_e32 v20, v20, v21
	v_and_b32_e32 v21, 0xffff0000, v59
	v_and_b32_e32 v23, 0xffff0000, v23
	v_add_f32_e32 v21, v21, v23
	v_cvt_pk_bf16_f32 v23, v20, v21
	v_mov_b32_e32 v20, v49
	v_mov_b32_e32 v21, v3
	v_lshlrev_b64 v[20:21], s1, v[20:21]
	v_min_u32_e32 v20, 1, v20
	v_or_b32_e32 v20, v21, v20
	v_cvt_f32_u32_e32 v20, v20
	v_cvt_f32_u32_e32 v21, v48
	s_sub_i32 s1, 32, s1
	v_lshlrev_b32_e32 v48, 16, v52
	v_ldexp_f32 v20, v20, s1
	v_and_b32_e32 v49, 0xffff0000, v52
	v_lshlrev_b32_e32 v52, 16, v53
	v_and_b32_e32 v53, 0xffff0000, v53
	v_fmac_f32_e32 v21, 0x4f800000, v20
	v_mul_f32_e32 v20, v49, v49
	v_mul_f32_e32 v56, v53, v53
	v_fmac_f32_e32 v20, v48, v48
	v_fmac_f32_e32 v56, v52, v52
	v_add_f32_e32 v20, v20, v56
	v_lshlrev_b32_e32 v56, 16, v54
	v_and_b32_e32 v54, 0xffff0000, v54
	v_mul_f32_e32 v57, v54, v54
	v_fmac_f32_e32 v57, v56, v56
	v_add_f32_e32 v20, v20, v57
	v_lshlrev_b32_e32 v57, 16, v55
	v_and_b32_e32 v55, 0xffff0000, v55
	v_mul_f32_e32 v58, v55, v55
	v_fmac_f32_e32 v58, v57, v57
	v_add_f32_e32 v20, v20, v58
	v_lshlrev_b32_e32 v58, 16, v44
	v_and_b32_e32 v44, 0xffff0000, v44
	v_mul_f32_e32 v59, v44, v44
	v_fmac_f32_e32 v59, v58, v58
	v_add_f32_e32 v20, v20, v59
	v_lshlrev_b32_e32 v59, 16, v45
	v_and_b32_e32 v45, 0xffff0000, v45
	v_mul_f32_e32 v60, v45, v45
	v_fmac_f32_e32 v60, v59, v59
	v_add_f32_e32 v20, v20, v60
	v_lshlrev_b32_e32 v60, 16, v46
	v_and_b32_e32 v46, 0xffff0000, v46
	v_mul_f32_e32 v61, v46, v46
	v_fmac_f32_e32 v61, v60, v60
	v_add_f32_e32 v20, v20, v61
	v_lshlrev_b32_e32 v61, 16, v47
	v_and_b32_e32 v47, 0xffff0000, v47
	v_mul_f32_e32 v62, v47, v47
	v_fmac_f32_e32 v62, v61, v61
	v_add_f32_e32 v20, v20, v62
	v_lshlrev_b32_e32 v62, 16, v40
	v_and_b32_e32 v40, 0xffff0000, v40
	v_mul_f32_e32 v63, v40, v40
	v_fmac_f32_e32 v63, v62, v62
	v_add_f32_e32 v20, v20, v63
	v_lshlrev_b32_e32 v63, 16, v41
	v_and_b32_e32 v41, 0xffff0000, v41
	v_mul_f32_e32 v64, v41, v41
	v_fmac_f32_e32 v64, v63, v63
	v_add_f32_e32 v20, v20, v64
	v_lshlrev_b32_e32 v64, 16, v42
	v_and_b32_e32 v42, 0xffff0000, v42
	v_mul_f32_e32 v65, v42, v42
	v_fmac_f32_e32 v65, v64, v64
	v_add_f32_e32 v20, v20, v65
	v_lshlrev_b32_e32 v65, 16, v43
	v_and_b32_e32 v43, 0xffff0000, v43
	v_mul_f32_e32 v66, v43, v43
	v_fmac_f32_e32 v66, v65, v65
	v_add_f32_e32 v20, v20, v66
	v_lshlrev_b32_e32 v66, 16, v36
	v_mul_f32_e32 v36, v67, v67
	v_fmac_f32_e32 v36, v66, v66
	v_add_f32_e32 v20, v20, v36
	v_mul_f32_e32 v36, v69, v69
	v_fmac_f32_e32 v36, v68, v68
	v_add_f32_e32 v20, v20, v36
	v_mul_f32_e32 v36, v71, v71
	v_fmac_f32_e32 v36, v70, v70
	v_add_f32_e32 v20, v20, v36
	v_mul_f32_e32 v36, v73, v73
	v_fmac_f32_e32 v36, v72, v72
	v_add_f32_e32 v20, v20, v36
	v_add_f32_e32 v20, v20, v32
	v_mul_f32_e32 v32, v77, v77
	v_fmac_f32_e32 v32, v76, v76
	v_add_f32_e32 v20, v20, v32
	v_mul_f32_e32 v32, v79, v79
	v_fmac_f32_e32 v32, v78, v78
	v_add_f32_e32 v20, v20, v32
	v_mul_f32_e32 v32, v81, v81
	v_fmac_f32_e32 v32, v80, v80
	v_add_f32_e32 v20, v20, v32
	v_add_f32_e32 v20, v20, v28
	v_mul_f32_e32 v28, v85, v85
	v_fmac_f32_e32 v28, v84, v84
	v_add_f32_e32 v20, v20, v28
	v_mul_f32_e32 v28, v87, v87
	v_fmac_f32_e32 v28, v86, v86
	v_add_f32_e32 v20, v20, v28
	v_mul_f32_e32 v28, v89, v89
	v_fmac_f32_e32 v28, v88, v88
	v_add_f32_e32 v20, v20, v28
	v_add_f32_e32 v20, v20, v24
	v_mul_f32_e32 v24, v93, v93
	v_fmac_f32_e32 v24, v92, v92
	v_add_f32_e32 v20, v20, v24
	v_mul_f32_e32 v24, v95, v95
	v_fmac_f32_e32 v24, v94, v94
	v_add_f32_e32 v20, v20, v24
	v_mul_f32_e32 v24, v97, v97
	v_fmac_f32_e32 v24, v96, v96
	v_and_b32_e32 v99, 0xffff0000, v50
	v_add_f32_e32 v20, v20, v24
	v_lshlrev_b32_e32 v98, 16, v50
	v_mul_f32_e32 v24, v99, v99
	v_fmac_f32_e32 v24, v98, v98
	v_and_b32_e32 v101, 0xffff0000, v51
	v_add_f32_e32 v20, v20, v24
	v_lshlrev_b32_e32 v100, 16, v51
	v_mul_f32_e32 v24, v101, v101
	v_and_b32_e32 v103, 0xffff0000, v22
	v_fmac_f32_e32 v24, v100, v100
	v_lshlrev_b32_e32 v102, 16, v22
	v_mul_f32_e32 v22, v103, v103
	v_add_f32_e32 v20, v20, v24
	v_fmac_f32_e32 v22, v102, v102
	v_and_b32_e32 v105, 0xffff0000, v23
	v_add_f32_e32 v20, v20, v22
	v_lshlrev_b32_e32 v104, 16, v23
	v_mul_f32_e32 v22, v105, v105
	v_fmac_f32_e32 v22, v104, v104
	v_add_f32_e32 v20, v20, v22
	v_mov_b32_e32 v22, v20
	s_nop 1
	v_permlane32_swap_b32_e32 v20, v22
	v_add_f32_e32 v20, v20, v22
	v_fmamk_f32 v21, v21, 0x2e000000, v200
	v_mul_f32_e32 v20, 0x3c000000, v20
	v_fmac_f32_e32 v20, 0x358637bd, v21
	v_rsq_f32_e32 v106, v20
	ds_read_b128 v[20:23], v141
	ds_read_b128 v[24:27], v141 offset:16
	v_mul_f32_e32 v28, v106, v48
	s_waitcnt lgkmcnt(1)
	v_mul_f32_e32 v20, v20, v28
	v_mul_f32_e32 v28, v106, v49
	v_mul_f32_e32 v21, v21, v28
	v_cvt_pk_bf16_f32 v20, v20, v21
	v_mul_f32_e32 v21, v106, v52
	v_mul_f32_e32 v21, v22, v21
	v_mul_f32_e32 v22, v106, v53
	v_mul_f32_e32 v22, v23, v22
	v_cvt_pk_bf16_f32 v21, v21, v22
	v_mul_f32_e32 v22, v106, v56
	v_mul_f32_e32 v23, v106, v54
	s_waitcnt lgkmcnt(0)
; #define LAS __attribute__((address_space(3)))
; __device__ __forceinline__ unsigned cvtpk(float lo, float hi) { unsigned r; asm volatile("v_cvt_pk_bf16_f32 %0, %1, %2" : "=v"(r) : "v"(lo), "v"(hi)); return r; }
; template <class P> __device__ __forceinline__ void attn_phase(P pol, LAS unsigned char* L, int G) {
;     ...
;       const float rq = __builtin_amdgcn_rsqf(ss * (1.f / HD) + RMS_EPS * varq);
; #pragma unroll
;       for (int d0 = 0; d0 < 8; ++d0) { const f32x4 g0 = *(const LAS f32x4*)(gq + d0 * 16 + hi * 8), g1 = *(const LAS f32x4*)(gq + d0 * 16 + hi * 8 + 4); u32x4 w;
;         w[0] = cvtpk(bflo(qw[d0][0]) * rq * g0[0], bfhi(qw[d0][0]) * rq * g0[1]); w[1] = cvtpk(bflo(qw[d0][1]) * rq * g0[2], bfhi(qw[d0][1]) * rq * g0[3]);
;         w[2] = cvtpk(bflo(qw[d0][2]) * rq * g1[0], bfhi(qw[d0][2]) * rq * g1[1]); w[3] = cvtpk(bflo(qw[d0][3]) * rq * g1[2], bfhi(qw[d0][3]) * rq * g1[3]);
;         qf[d0] = __builtin_bit_cast(bf16x8, w); } }
	v_mul_f32_e32 v22, v24, v22
	v_mul_f32_e32 v23, v25, v23
	v_cvt_pk_bf16_f32 v22, v22, v23
	v_mul_f32_e32 v23, v106, v57
	v_mul_f32_e32 v24, v106, v55
	v_mul_f32_e32 v23, v26, v23
	v_mul_f32_e32 v24, v27, v24
	v_cvt_pk_bf16_f32 v23, v23, v24
	ds_read_b128 v[24:27], v141 offset:64
	ds_read_b128 v[28:31], v141 offset:80
	v_mul_f32_e32 v32, v106, v58
	v_mul_f32_e32 v36, v106, v62
	v_mul_f32_e32 v48, v106, v82
	s_waitcnt lgkmcnt(1)
	v_mul_f32_e32 v24, v32, v24
	v_mul_f32_e32 v32, v106, v44
	v_mul_f32_e32 v25, v32, v25
	v_cvt_pk_bf16_f32 v24, v24, v25
	v_mul_f32_e32 v25, v106, v59
	v_mul_f32_e32 v25, v25, v26
	v_mul_f32_e32 v26, v106, v45
	v_mul_f32_e32 v26, v26, v27
	v_cvt_pk_bf16_f32 v25, v25, v26
	v_mul_f32_e32 v26, v106, v60
	v_mul_f32_e32 v27, v106, v46
	s_waitcnt lgkmcnt(0)
	v_mul_f32_e32 v26, v26, v28
	v_mul_f32_e32 v27, v27, v29
	v_cvt_pk_bf16_f32 v26, v26, v27
	v_mul_f32_e32 v27, v106, v61
	v_mul_f32_e32 v28, v106, v47
	v_mul_f32_e32 v27, v27, v30
	v_mul_f32_e32 v28, v28, v31
	v_cvt_pk_bf16_f32 v27, v27, v28
	ds_read_b128 v[28:31], v141 offset:128
	ds_read_b128 v[32:35], v141 offset:144
	v_mul_f32_e32 v44, v106, v74
	v_mul_f32_e32 v52, v106, v90
	v_mul_f32_e32 v56, v106, v98
	s_waitcnt lgkmcnt(1)
	v_mul_f32_e32 v28, v36, v28
	v_mul_f32_e32 v36, v106, v40
	v_mul_f32_e32 v29, v36, v29
	v_cvt_pk_bf16_f32 v28, v28, v29
	v_mul_f32_e32 v29, v106, v63
	v_mul_f32_e32 v29, v29, v30
	v_mul_f32_e32 v30, v106, v41
	v_mul_f32_e32 v30, v30, v31
	v_cvt_pk_bf16_f32 v29, v29, v30
	v_mul_f32_e32 v30, v106, v64
	v_mul_f32_e32 v31, v106, v42
	s_waitcnt lgkmcnt(0)
	v_mul_f32_e32 v30, v30, v32
	v_mul_f32_e32 v31, v31, v33
	v_cvt_pk_bf16_f32 v30, v30, v31
	v_mul_f32_e32 v31, v106, v65
	v_mul_f32_e32 v32, v106, v43
	v_mul_f32_e32 v31, v31, v34
	v_mul_f32_e32 v32, v32, v35
	v_cvt_pk_bf16_f32 v31, v31, v32
	ds_read_b128 v[32:35], v141 offset:192
	ds_read_b128 v[36:39], v141 offset:208
	v_mul_f32_e32 v40, v106, v66
	v_mov_b32_e32 v57, v159
	v_mov_b32_e32 v58, v159
	s_waitcnt lgkmcnt(1)
	v_mul_f32_e32 v32, v40, v32
	v_mul_f32_e32 v40, v106, v67
	v_mul_f32_e32 v33, v40, v33
	v_cvt_pk_bf16_f32 v32, v32, v33
	v_mul_f32_e32 v33, v106, v68
	v_mul_f32_e32 v33, v33, v34
	v_mul_f32_e32 v34, v106, v69
	v_mul_f32_e32 v34, v34, v35
	v_cvt_pk_bf16_f32 v33, v33, v34
	v_mul_f32_e32 v34, v106, v70
	v_mul_f32_e32 v35, v106, v71
	s_waitcnt lgkmcnt(0)
	v_mul_f32_e32 v34, v34, v36
	v_mul_f32_e32 v35, v35, v37
	v_cvt_pk_bf16_f32 v34, v34, v35
	v_mul_f32_e32 v35, v106, v72
	v_mul_f32_e32 v36, v106, v73
	v_mul_f32_e32 v35, v35, v38
	v_mul_f32_e32 v36, v36, v39
	v_cvt_pk_bf16_f32 v35, v35, v36
	ds_read_b128 v[36:39], v141 offset:256
	ds_read_b128 v[40:43], v141 offset:272
	v_mov_b32_e32 v59, v159
	v_mov_b32_e32 v60, v159
	v_mov_b32_e32 v61, v159
	s_waitcnt lgkmcnt(1)
	v_mul_f32_e32 v36, v44, v36
	v_mul_f32_e32 v44, v106, v75
	v_mul_f32_e32 v37, v44, v37
	v_cvt_pk_bf16_f32 v36, v36, v37
	v_mul_f32_e32 v37, v106, v76
	v_mul_f32_e32 v37, v37, v38
	v_mul_f32_e32 v38, v106, v77
	v_mul_f32_e32 v38, v38, v39
	v_cvt_pk_bf16_f32 v37, v37, v38
	v_mul_f32_e32 v38, v106, v78
	v_mul_f32_e32 v39, v106, v79
	s_waitcnt lgkmcnt(0)
	v_mul_f32_e32 v38, v38, v40
	v_mul_f32_e32 v39, v39, v41
	v_cvt_pk_bf16_f32 v38, v38, v39
	v_mul_f32_e32 v39, v106, v80
	v_mul_f32_e32 v40, v106, v81
	v_mul_f32_e32 v39, v39, v42
	v_mul_f32_e32 v40, v40, v43
	v_cvt_pk_bf16_f32 v39, v39, v40
	ds_read_b128 v[40:43], v141 offset:320
	ds_read_b128 v[44:47], v141 offset:336
	v_mov_b32_e32 v62, v159
	v_mov_b32_e32 v63, v159
	v_mov_b32_e32 v64, v159
	s_waitcnt lgkmcnt(1)
	v_mul_f32_e32 v40, v48, v40
	v_mul_f32_e32 v48, v106, v83
	v_mul_f32_e32 v41, v48, v41
	v_cvt_pk_bf16_f32 v40, v40, v41
	v_mul_f32_e32 v41, v106, v84
	v_mul_f32_e32 v41, v41, v42
	v_mul_f32_e32 v42, v106, v85
	v_mul_f32_e32 v42, v42, v43
	v_cvt_pk_bf16_f32 v41, v41, v42
	v_mul_f32_e32 v42, v106, v86
	v_mul_f32_e32 v43, v106, v87
	s_waitcnt lgkmcnt(0)
	v_mul_f32_e32 v42, v42, v44
	v_mul_f32_e32 v43, v43, v45
	v_cvt_pk_bf16_f32 v42, v42, v43
	v_mul_f32_e32 v43, v106, v88
	v_mul_f32_e32 v44, v106, v89
	v_mul_f32_e32 v43, v43, v46
	v_mul_f32_e32 v44, v44, v47
	v_cvt_pk_bf16_f32 v43, v43, v44
	ds_read_b128 v[44:47], v141 offset:384
	ds_read_b128 v[48:51], v141 offset:400
	v_mov_b32_e32 v65, v159
	v_mov_b32_e32 v66, v159
	v_mov_b32_e32 v67, v159
	s_waitcnt lgkmcnt(1)
	v_mul_f32_e32 v44, v52, v44
	v_mul_f32_e32 v52, v106, v91
	v_mul_f32_e32 v45, v52, v45
	v_cvt_pk_bf16_f32 v44, v44, v45
	v_mul_f32_e32 v45, v106, v92
	v_mul_f32_e32 v45, v45, v46
	v_mul_f32_e32 v46, v106, v93
	v_mul_f32_e32 v46, v46, v47
	v_cvt_pk_bf16_f32 v45, v45, v46
	v_mul_f32_e32 v46, v106, v94
	v_mul_f32_e32 v47, v106, v95
	s_waitcnt lgkmcnt(0)
	v_mul_f32_e32 v46, v46, v48
	v_mul_f32_e32 v47, v47, v49
	v_cvt_pk_bf16_f32 v46, v46, v47
	v_mul_f32_e32 v47, v106, v96
	v_mul_f32_e32 v48, v106, v97
	v_mul_f32_e32 v47, v47, v50
	v_mul_f32_e32 v48, v48, v51
	v_cvt_pk_bf16_f32 v47, v47, v48
	ds_read_b128 v[48:51], v141 offset:448
	ds_read_b128 v[52:55], v141 offset:464
	s_waitcnt lgkmcnt(1)
; #define LAS __attribute__((address_space(3)))
; __device__ __forceinline__ unsigned cvtpk(float lo, float hi) { unsigned r; asm volatile("v_cvt_pk_bf16_f32 %0, %1, %2" : "=v"(r) : "v"(lo), "v"(hi)); return r; }
; __device__ __forceinline__ float row16_sum(float v) { v += dppf<0xB1>(v); v += dppf<0x4E>(v); v += dppf<0x141>(v); v += dppf<0x140>(v); return v; }
;   __device__ __forceinline__ float tb_fin(int x, float v) const { return (x >= 0 && x <= 128) ? v * LOG2E : NEGM; }
; __device__ __forceinline__ u32x4 knorm(u32x4 w, float epsv) {
;   float f[8]; float ss = 0.f;
; #pragma unroll
;   for (int e = 0; e < 4; ++e) { f[2 * e] = bflo(w[e]); f[2 * e + 1] = bfhi(w[e]); ss += f[2 * e] * f[2 * e] + f[2 * e + 1] * f[2 * e + 1]; }
;   ss = row16_sum(ss);
;   const float rs = __builtin_amdgcn_rsqf(ss * (1.f / HD) + epsv);
;   u32x4 o;
; #pragma unroll
;   for (int e = 0; e < 4; ++e) o[e] = cvtpk(f[2 * e] * rs, f[2 * e + 1] * rs);
;   return o;
; }
; template <class P> __device__ __forceinline__ void attn_phase(P pol, LAS unsigned char* L, int G) {
;     ...
;     const LAS unsigned char* const qst = ost + lane * 16;
; #pragma unroll
;     for (int d0 = 0; d0 < 8; ++d0) *(LAS bf16x8*)(ost + d0 * 1024 + lane * 16) = qf[d0];
;     if (P::HAS_BIAS) { const int x = P::TB_LO + tid; if (x < P::TB_HI) tb[x] = pol.tb_fin(x, tbv); }
;     SWRITE(0);
;     __syncthreads();
;     constexpr float m_reg = 0.f; float l_reg = 0.f; f32x16 o[4] = {};
	v_mul_f32_e32 v48, v56, v48
	v_mul_f32_e32 v56, v106, v99
	v_mul_f32_e32 v49, v56, v49
	v_cvt_pk_bf16_f32 v48, v48, v49
	v_mul_f32_e32 v49, v106, v100
	v_mul_f32_e32 v49, v49, v50
	v_mul_f32_e32 v50, v106, v101
	v_mul_f32_e32 v50, v50, v51
	v_cvt_pk_bf16_f32 v49, v49, v50
	v_mul_f32_e32 v50, v106, v102
	v_mul_f32_e32 v51, v106, v103
	s_waitcnt lgkmcnt(0)
	v_mul_f32_e32 v50, v50, v52
	v_mul_f32_e32 v51, v51, v53
	v_cvt_pk_bf16_f32 v50, v50, v51
	v_mul_f32_e32 v51, v106, v104
	v_mul_f32_e32 v51, v51, v54
	v_mul_f32_e32 v52, v106, v105
	v_mul_f32_e32 v52, v52, v55
	v_cvt_pk_bf16_f32 v51, v51, v52
	ds_write_b128 v158, v[20:23]
	ds_write_b128 v158, v[24:27] offset:1024
	ds_write_b128 v158, v[28:31] offset:2048
	ds_write_b128 v158, v[32:35] offset:3072
	ds_write_b128 v158, v[36:39] offset:4096
	ds_write_b128 v158, v[40:43] offset:5120
	ds_write_b128 v158, v[44:47] offset:6144
	ds_write_b128 v158, v[48:51] offset:7168
	v_add_u32_e32 v20, 0, v118
	ds_write_b128 v20, v[12:15]
	ds_write_b128 v20, v[16:19] offset:8192
	v_and_b32_e32 v15, 0xffff0000, v8
	v_and_b32_e32 v17, 0xffff0000, v9
	v_lshlrev_b32_e32 v14, 16, v8
	v_mul_f32_e32 v8, v15, v15
	v_lshlrev_b32_e32 v16, 16, v9
	v_mul_f32_e32 v9, v17, v17
	v_fmac_f32_e32 v8, v14, v14
	v_fmac_f32_e32 v9, v16, v16
	v_lshlrev_b32_e32 v13, 16, v11
	v_lshlrev_b32_e32 v12, 16, v10
	v_and_b32_e32 v11, 0xffff0000, v11
	v_and_b32_e32 v10, 0xffff0000, v10
	v_add_f32_e32 v18, v8, v9
	v_pk_mul_f32 v[8:9], v[10:11], v[10:11]
	v_mov_b32_e32 v19, v159
	v_pk_fma_f32 v[8:9], v[12:13], v[12:13], v[8:9]
	v_mov_b32_e32 v20, 0
	v_add_f32_e32 v8, v8, v18
	v_add_f32_e32 v8, v9, v8
	v_mov_b32_e32 v21, v159
	v_mov_b32_e32 v22, v159
	v_add_f32_dpp v8, v8, v8 quad_perm:[1,0,3,2] row_mask:0xf bank_mask:0xf bound_ctrl:1
	v_mov_b32_e32 v23, v159
	v_mov_b32_e32 v24, v159
	v_add_f32_dpp v8, v8, v8 quad_perm:[2,3,0,1] row_mask:0xf bank_mask:0xf bound_ctrl:1
	v_mov_b32_e32 v25, v159
	v_mov_b32_e32 v26, v159
	v_add_f32_dpp v8, v8, v8 row_half_mirror row_mask:0xf bank_mask:0xf bound_ctrl:1
	v_mov_b32_e32 v27, v159
	v_mov_b32_e32 v28, v159
	v_add_f32_dpp v8, v8, v8 row_mirror row_mask:0xf bank_mask:0xf bound_ctrl:1
	v_fmamk_f32 v8, v8, 0x3c000000, v200
	v_rsq_f32_e32 v18, v8
	v_mov_b32_e32 v29, v159
	v_mov_b32_e32 v30, v159
	v_mov_b32_e32 v31, v159
	v_mul_f32_e32 v8, v18, v14
	v_mul_f32_e32 v9, v18, v15
	v_cvt_pk_bf16_f32 v8, v8, v9
	v_mul_f32_e32 v9, v18, v16
	v_mul_f32_e32 v12, v18, v12
	v_mul_f32_e32 v10, v18, v10
	v_mul_f32_e32 v14, v18, v17
	v_cvt_pk_bf16_f32 v9, v9, v14
	v_cvt_pk_bf16_f32 v10, v12, v10
	v_mul_f32_e32 v12, v18, v13
	v_mul_f32_e32 v11, v18, v11
	v_cvt_pk_bf16_f32 v11, v12, v11
	v_add_u32_e32 v12, 0, v119
	ds_write_b128 v12, v[8:11] offset:32768
	v_and_b32_e32 v11, 0xffff0000, v4
	v_and_b32_e32 v14, 0xffff0000, v5
	v_lshlrev_b32_e32 v10, 16, v4
	v_mul_f32_e32 v4, v11, v11
	v_lshlrev_b32_e32 v13, 16, v5
	v_mul_f32_e32 v5, v14, v14
	v_fmac_f32_e32 v4, v10, v10
	v_fmac_f32_e32 v5, v13, v13
	v_lshlrev_b32_e32 v9, 16, v7
	v_lshlrev_b32_e32 v8, 16, v6
	v_and_b32_e32 v7, 0xffff0000, v7
	v_and_b32_e32 v6, 0xffff0000, v6
	v_add_f32_e32 v15, v4, v5
	v_pk_mul_f32 v[4:5], v[6:7], v[6:7]
	v_mov_b32_e32 v16, v159
	v_pk_fma_f32 v[4:5], v[8:9], v[8:9], v[4:5]
	v_mov_b32_e32 v17, v159
	v_add_f32_e32 v4, v4, v15
	v_add_f32_e32 v4, v5, v4
	v_mov_b32_e32 v18, v159
	v_mov_b32_e32 v32, v159
	v_add_f32_dpp v4, v4, v4 quad_perm:[1,0,3,2] row_mask:0xf bank_mask:0xf bound_ctrl:1
	v_mov_b32_e32 v33, v159
	v_mov_b32_e32 v34, v159
	v_add_f32_dpp v4, v4, v4 quad_perm:[2,3,0,1] row_mask:0xf bank_mask:0xf bound_ctrl:1
	v_mov_b32_e32 v35, v159
	v_mov_b32_e32 v36, 0
	v_add_f32_dpp v4, v4, v4 row_half_mirror row_mask:0xf bank_mask:0xf bound_ctrl:1
	v_mov_b32_e32 v37, v159
	v_mov_b32_e32 v38, v159
	v_add_f32_dpp v4, v4, v4 row_mirror row_mask:0xf bank_mask:0xf bound_ctrl:1
	v_fmamk_f32 v4, v4, 0x3c000000, v200
	v_rsq_f32_e32 v15, v4
	v_mov_b32_e32 v39, v159
	v_mov_b32_e32 v40, v159
	v_mov_b32_e32 v41, v159
	v_mul_f32_e32 v4, v15, v10
	v_mul_f32_e32 v5, v15, v11
	v_cvt_pk_bf16_f32 v4, v4, v5
	v_mul_f32_e32 v5, v15, v13
	v_mul_f32_e32 v8, v15, v8
	v_mul_f32_e32 v6, v15, v6
	v_mul_f32_e32 v7, v15, v7
	v_mul_f32_e32 v10, v15, v14
	v_cvt_pk_bf16_f32 v5, v5, v10
	v_cvt_pk_bf16_f32 v6, v8, v6
	v_mul_f32_e32 v8, v15, v9
	v_cvt_pk_bf16_f32 v7, v8, v7
	ds_write_b128 v12, v[4:7] offset:40960
	v_mov_b32_e32 v4, 0
	v_mov_b32_e32 v5, v159
	v_mov_b32_e32 v6, v159
	v_mov_b32_e32 v7, v159
	v_mov_b32_e32 v8, v159
	v_mov_b32_e32 v9, v159
	v_mov_b32_e32 v10, v159
	v_mov_b32_e32 v11, v159
	v_mov_b32_e32 v12, v159
	v_mov_b32_e32 v13, v159
	v_mov_b32_e32 v14, v159
	v_mov_b32_e32 v15, v159
	v_mov_b32_e32 v42, v159
	v_mov_b32_e32 v43, v159
	v_mov_b32_e32 v44, v159
	v_mov_b32_e32 v45, v159
	v_mov_b32_e32 v46, v159
	v_mov_b32_e32 v47, v159
	v_mov_b32_e32 v48, v159
	v_mov_b32_e32 v49, v159
	v_mov_b32_e32 v50, v159
	v_mov_b32_e32 v51, v159
	v_mov_b32_e32 v52, 0
	v_mov_b32_e32 v53, v159
	v_mov_b32_e32 v54, v159
	v_mov_b32_e32 v55, v159
	v_mov_b32_e32 v56, v159
	s_waitcnt lgkmcnt(0)
	s_barrier
